# speedup vs baseline: 1.0020x; 1.0020x over previous
; #define PG8_STAGE(bufoff, gbase, voff) do { _Pragma("unroll") for (int _i = 0; _i < 2; ++_i) \
;         __builtin_amdgcn_global_load_lds((const unsigned*)((const char*)(gbase) + (voff)[_i]), (LAS unsigned*)(lds + (bufoff) + ldsw + _i * 8192), 16, 0, 0); } while (0)
; #define PG8_WAIT_V(n) asm volatile("s_waitcnt vmcnt(" #n ")" ::: "memory")
; #define PG8_BAR __builtin_amdgcn_s_barrier()
; __device__ __forceinline__ void gemm_phase(LAS unsigned char* lds, const GemmD& g) {
;     ...
;     f32x4 acc[2][2][4][2];
; #pragma unroll
;     for (int a = 0; a < 2; ++a)
; #pragma unroll
;         for (int b = 0; b < 2; ++b)
; #pragma unroll
;             for (int m = 0; m < 4; ++m)
; #pragma unroll
;                 for (int n = 0; n < 2; ++n) acc[a][b][m][n] = (f32x4){0.f, 0.f, 0.f, 0.f};
;     bf16x8 At[4][2], B0[2][2], B1[2][2];
;     const char* cA = (const char*)g.A + (size_t)cur.pm * tstep + (size_t)cur.k0 * kstep; const char* cB = (const char*)g.Bt + (size_t)cur.pn * tstep + (size_t)cur.k0 * kstep;
;     PG8_STAGE(PG8_SB(0, 0), cB, voffB); PG8_STAGE(PG8_SA(0, 0), cA, voffA); PG8_STAGE(PG8_SB(0, 1), cB + hstep, voffB); PG8_STAGE(PG8_SA(0, 1), cA + hstep, voffA);
;     if (wr == 1) PG8_BAR;
;     PG8_WAIT_V(4); PG8_BAR;
;     PG8_STAGE(PG8_SB(1, 0), cB + kstep, voffB); PG8_STAGE(PG8_SA(1, 0), cA + kstep, voffA); PG8_STAGE(PG8_SB(1, 1), cB + hstep + kstep, voffB);
;     PG8_WAIT_V(6); PG8_BAR;
;     for (;;) {
;         const bool has_next = unit_get(g, nM, nN, G, cblk, ui + 1, nxt);
;         const char* nA = has_next ? (const char*)g.A + (size_t)nxt.pm * tstep + (size_t)nxt.k0 * kstep : cA; const char* nB = has_next ? (const char*)g.Bt + (size_t)nxt.pn * tstep + (size_t)nxt.k0 * kstep : cB;
;         const int nt = cur.nt;
;         for (int t = 0; t < nt; t += 2) {
.LBB0_144:
	v_lshl_add_u64 v[132:133], v[2:3], 0, s[46:47]
	v_mov_b32_e32 v2, 0
	v_add_u32_e32 v135, -2, v134
	v_lshl_add_u64 v[130:131], v[4:5], 0, s[44:45]
	s_mov_b32 s4, 0
	v_mov_b32_e32 v3, v2
	v_mov_b32_e32 v4, v2
	v_mov_b32_e32 v5, v2
	v_mov_b32_e32 v6, v2
	v_mov_b32_e32 v7, v2
	v_mov_b32_e32 v8, v2
	v_mov_b32_e32 v9, v2
	v_mov_b32_e32 v18, v2
	v_mov_b32_e32 v19, v2
	v_mov_b32_e32 v20, v2
	v_mov_b32_e32 v21, v2
	v_mov_b32_e32 v22, v2
	v_mov_b32_e32 v23, v2
	v_mov_b32_e32 v24, v2
	v_mov_b32_e32 v25, v2
	v_mov_b32_e32 v34, v2
	v_mov_b32_e32 v35, v2
	v_mov_b32_e32 v36, v2
	v_mov_b32_e32 v37, v2
	v_mov_b32_e32 v38, v2
	v_mov_b32_e32 v39, v2
	v_mov_b32_e32 v40, v2
	v_mov_b32_e32 v41, v2
	v_mov_b32_e32 v50, v2
	v_mov_b32_e32 v51, v2
	v_mov_b32_e32 v52, v2
	v_mov_b32_e32 v53, v2
	v_mov_b32_e32 v54, v2
	v_mov_b32_e32 v55, v2
	v_mov_b32_e32 v56, v2
	v_mov_b32_e32 v57, v2
	v_mov_b32_e32 v10, v2
	v_mov_b32_e32 v11, v2
	v_mov_b32_e32 v12, v2
	v_mov_b32_e32 v13, v2
	v_mov_b32_e32 v14, v2
	v_mov_b32_e32 v15, v2
	v_mov_b32_e32 v16, v2
	v_mov_b32_e32 v17, v2
	v_mov_b32_e32 v26, v2
	v_mov_b32_e32 v27, v2
	v_mov_b32_e32 v28, v2
	v_mov_b32_e32 v29, v2
	v_mov_b32_e32 v30, v2
	v_mov_b32_e32 v31, v2
	v_mov_b32_e32 v32, v2
	v_mov_b32_e32 v33, v2
	v_mov_b32_e32 v42, v2
	v_mov_b32_e32 v43, v2
	v_mov_b32_e32 v44, v2
	v_mov_b32_e32 v45, v2
	v_mov_b32_e32 v46, v2
	v_mov_b32_e32 v47, v2
	v_mov_b32_e32 v48, v2
	v_mov_b32_e32 v49, v2
	v_mov_b32_e32 v58, v2
	v_mov_b32_e32 v59, v2
	v_mov_b32_e32 v60, v2
	v_mov_b32_e32 v61, v2
	v_mov_b32_e32 v62, v2
	v_mov_b32_e32 v63, v2
	v_mov_b32_e32 v64, v2
	v_mov_b32_e32 v65, v2
	v_mov_b32_e32 v66, v2
	v_mov_b32_e32 v67, v2
	v_mov_b32_e32 v68, v2
	v_mov_b32_e32 v69, v2
	v_mov_b32_e32 v70, v2
	v_mov_b32_e32 v71, v2
	v_mov_b32_e32 v72, v2
	v_mov_b32_e32 v73, v2
	s_waitcnt vmcnt(0)
	v_mov_b32_e32 v82, v2
	v_mov_b32_e32 v83, v2
	v_mov_b32_e32 v84, v2
	v_mov_b32_e32 v85, v2
	v_mov_b32_e32 v86, v2
	v_mov_b32_e32 v87, v2
	v_mov_b32_e32 v88, v2
	v_mov_b32_e32 v89, v2
	v_mov_b32_e32 v98, v2
	v_mov_b32_e32 v99, v2
	v_mov_b32_e32 v100, v2
	v_mov_b32_e32 v101, v2
	v_mov_b32_e32 v102, v2
	v_mov_b32_e32 v103, v2
	v_mov_b32_e32 v104, v2
	v_mov_b32_e32 v105, v2
	v_mov_b32_e32 v114, v2
	v_mov_b32_e32 v115, v2
	v_mov_b32_e32 v116, v2
	v_mov_b32_e32 v117, v2
	v_mov_b32_e32 v118, v2
	v_mov_b32_e32 v119, v2
	v_mov_b32_e32 v120, v2
	v_mov_b32_e32 v121, v2
	v_mov_b32_e32 v74, v2
	v_mov_b32_e32 v75, v2
	v_mov_b32_e32 v76, v2
	v_mov_b32_e32 v77, v2
	v_mov_b32_e32 v78, v2
	v_mov_b32_e32 v79, v2
	v_mov_b32_e32 v80, v2
	v_mov_b32_e32 v81, v2
	v_mov_b32_e32 v90, v2
	v_mov_b32_e32 v91, v2
	v_mov_b32_e32 v92, v2
	v_mov_b32_e32 v93, v2
	v_mov_b32_e32 v94, v2
	v_mov_b32_e32 v95, v2
	v_mov_b32_e32 v96, v2
	v_mov_b32_e32 v97, v2
	v_mov_b32_e32 v106, v2
	v_mov_b32_e32 v107, v2
	v_mov_b32_e32 v108, v2
	v_mov_b32_e32 v109, v2
	v_mov_b32_e32 v110, v2
	v_mov_b32_e32 v111, v2
	v_mov_b32_e32 v112, v2
	v_mov_b32_e32 v113, v2
	v_mov_b32_e32 v122, v2
	v_mov_b32_e32 v123, v2
	v_mov_b32_e32 v124, v2
	v_mov_b32_e32 v125, v2
	v_mov_b32_e32 v126, v2
	v_mov_b32_e32 v127, v2
	v_mov_b32_e32 v128, v2
	v_mov_b32_e32 v129, v2
	v_readfirstlane_b32 s98, v130
	v_readfirstlane_b32 s99, v131
	v_readfirstlane_b32 s100, v132
	v_readfirstlane_b32 s101, v133
	v_add_u32_e32 v242, s72, v172
	v_add_u32_e32 v243, s72, v168
	v_add_u32_e32 v244, 0x10000, v229
	v_add_u32_e32 v245, 0x14000, v229
	v_add_u32_e32 v246, 0x18000, v229
	v_add_u32_e32 v247, 0x1c000, v229
	s_branch .Lkl_body
.LBB0_145:
	s_barrier

; #define PG8_STAGE(bufoff, gbase, voff) do { _Pragma("unroll") for (int _i = 0; _i < 2; ++_i) \
;         __builtin_amdgcn_global_load_lds((const unsigned*)((const char*)(gbase) + (voff)[_i]), (LAS unsigned*)(lds + (bufoff) + ldsw + _i * 8192), 16, 0, 0); } while (0)
; #define PG8_LDA(dst, b, h) do { _Pragma("unroll") for (int m = 0; m < 4; ++m) _Pragma("unroll") for (int k = 0; k < 2; ++k) dst[m][k] = *(const LAS bf16x8*)(lds + PG8_SA(b, h) + aoff + m * 2048 + k * 1024); } while (0)
; #define PG8_LDB(dst, b, h) do { _Pragma("unroll") for (int n = 0; n < 2; ++n) _Pragma("unroll") for (int k = 0; k < 2; ++k) dst[n][k] = *(const LAS bf16x8*)(lds + PG8_SB(b, h) + boff + n * 2048 + k * 1024); } while (0)
; #define PG8_MMA(ai, bj, At, Bt) do { __builtin_amdgcn_s_setprio(1); _Pragma("unroll") for (int m = 0; m < 4; ++m) _Pragma("unroll") for (int n = 0; n < 2; ++n) _Pragma("unroll") for (int k = 0; k < 2; ++k) \
;         acc[ai][bj][m][n] = __builtin_amdgcn_mfma_f32_16x16x32_bf16(Bt[n][k], At[m][k], acc[ai][bj][m][n], 0, 0, 0); __builtin_amdgcn_s_setprio(0); } while (0)
; #define PG8_WAIT_V(n) asm volatile("s_waitcnt vmcnt(" #n ")" ::: "memory")
; #define PG8_WAIT_L(n) asm volatile("s_waitcnt lgkmcnt(" #n ")" ::: "memory")
; #define PG8_BAR __builtin_amdgcn_s_barrier()
; #define PG8_SCHED __builtin_amdgcn_sched_barrier(0)
; __device__ __forceinline__ void gemm_phase(LAS unsigned char* lds, const GemmD& g) {
;     ...
;             PG8_LDB(B1, 0, 1); PG8_STAGE(PG8_SB(0, 0), b2, voffB);
;             PG8_BAR; PG8_WAIT_L(0); PG8_MMA(0, 1, At, B1); PG8_BAR;
;             PG8_LDA(At, 0, 1); PG8_STAGE(PG8_SA(0, 0), a2, voffA);
;             PG8_BAR; PG8_WAIT_L(0); PG8_MMA(1, 0, At, B0); PG8_BAR; PG8_SCHED;
;             PG8_STAGE(PG8_SB(0, 1), b2 + hstep, voffB);
;             PG8_WAIT_V(6); PG8_BAR; PG8_MMA(1, 1, At, B1); PG8_BAR;
;             PG8_LDB(B0, 1, 0); PG8_SCHED; PG8_LDA(At, 1, 0); PG8_STAGE(PG8_SA(0, 1), a2 + hstep, voffA);
;             PG8_WAIT_L(8); PG8_BAR; PG8_WAIT_L(0); PG8_MMA(0, 0, At, B0); PG8_BAR; PG8_SCHED;
.Lkl_ptr_done:
	s_add_i32 s4, 0, 0x14000
	s_add_i32 s6, s6, s87
	s_mov_b32 m0, s6
	ds_read_b128 v[204:207], v245
	ds_read_b128 v[208:211], v245 offset:1024
	ds_read_b128 v[234:237], v245 offset:2048
	ds_read_b128 v[238:241], v245 offset:3072
	global_load_lds_dwordx4 v172, s[100:101]
	s_add_i32 m0, s6, 0x2000
	s_nop 0
	global_load_lds_dwordx4 v168, s[100:101]
	s_barrier
	s_waitcnt lgkmcnt(0)
	v_mfma_f32_16x16x32_bf16 v[118:121], v[204:207], v[152:155], v[118:121]
	v_mfma_f32_16x16x32_bf16 v[114:117], v[234:237], v[152:155], v[114:117]
	v_mfma_f32_16x16x32_bf16 v[102:105], v[204:207], v[160:163], v[102:105]
	v_mfma_f32_16x16x32_bf16 v[98:101], v[234:237], v[160:163], v[98:101]
	v_mfma_f32_16x16x32_bf16 v[86:89], v[204:207], v[188:191], v[86:89]
	v_mfma_f32_16x16x32_bf16 v[82:85], v[234:237], v[188:191], v[82:85]
	v_mfma_f32_16x16x32_bf16 v[70:73], v[204:207], v[196:199], v[70:73]
	v_mfma_f32_16x16x32_bf16 v[66:69], v[234:237], v[196:199], v[66:69]
	v_mfma_f32_16x16x32_bf16 v[118:121], v[208:211], v[156:159], v[118:121]
	v_mfma_f32_16x16x32_bf16 v[114:117], v[238:241], v[156:159], v[114:117]
	v_mfma_f32_16x16x32_bf16 v[102:105], v[208:211], v[184:187], v[102:105]
	v_mfma_f32_16x16x32_bf16 v[98:101], v[238:241], v[184:187], v[98:101]
	v_mfma_f32_16x16x32_bf16 v[86:89], v[208:211], v[192:195], v[86:89]
	v_mfma_f32_16x16x32_bf16 v[82:85], v[238:241], v[192:195], v[82:85]
	v_mfma_f32_16x16x32_bf16 v[70:73], v[208:211], v[200:203], v[70:73]
	v_mfma_f32_16x16x32_bf16 v[66:69], v[238:241], v[200:203], v[66:69]
	s_barrier
	s_mov_b32 m0, s2
	ds_read_b128 v[152:155], v233 offset:16384
	ds_read_b128 v[156:159], v233 offset:17408
	ds_read_b128 v[160:163], v233 offset:18432
	ds_read_b128 v[184:187], v233 offset:19456
	ds_read_b128 v[188:191], v233 offset:20480
	ds_read_b128 v[192:195], v233 offset:21504
	ds_read_b128 v[196:199], v233 offset:22528
	ds_read_b128 v[200:203], v233 offset:23552
	global_load_lds_dwordx4 v170, s[98:99]
	s_mov_b32 m0, s3
	s_nop 0
	global_load_lds_dwordx4 v166, s[98:99]
	s_barrier
	s_waitcnt lgkmcnt(0)
	v_mfma_f32_16x16x32_bf16 v[62:65], v[136:139], v[152:155], v[62:65]
	v_mfma_f32_16x16x32_bf16 v[58:61], v[144:147], v[152:155], v[58:61]
	v_mfma_f32_16x16x32_bf16 v[46:49], v[136:139], v[160:163], v[46:49]
	v_mfma_f32_16x16x32_bf16 v[42:45], v[144:147], v[160:163], v[42:45]
	v_mfma_f32_16x16x32_bf16 v[30:33], v[136:139], v[188:191], v[30:33]
	v_mfma_f32_16x16x32_bf16 v[26:29], v[144:147], v[188:191], v[26:29]
	v_mfma_f32_16x16x32_bf16 v[14:17], v[136:139], v[196:199], v[14:17]
	v_mfma_f32_16x16x32_bf16 v[10:13], v[144:147], v[196:199], v[10:13]
	v_mfma_f32_16x16x32_bf16 v[62:65], v[140:143], v[156:159], v[62:65]
	v_mfma_f32_16x16x32_bf16 v[58:61], v[148:151], v[156:159], v[58:61]
	v_mfma_f32_16x16x32_bf16 v[46:49], v[140:143], v[184:187], v[46:49]
	v_mfma_f32_16x16x32_bf16 v[42:45], v[148:151], v[184:187], v[42:45]
	v_mfma_f32_16x16x32_bf16 v[30:33], v[140:143], v[192:195], v[30:33]
	v_mfma_f32_16x16x32_bf16 v[26:29], v[148:151], v[192:195], v[26:29]
	v_mfma_f32_16x16x32_bf16 v[14:17], v[140:143], v[200:203], v[14:17]
	v_mfma_f32_16x16x32_bf16 v[10:13], v[148:151], v[200:203], v[10:13]
	s_barrier
	s_add_i32 s4, s4, s87
	s_mov_b32 m0, s4
	s_nop 0
	global_load_lds_dwordx4 v242, s[100:101]
	s_add_i32 m0, s4, 0x2000
	s_nop 0
	global_load_lds_dwordx4 v243, s[100:101]
	s_waitcnt vmcnt(6)
	s_barrier
	v_mfma_f32_16x16x32_bf16 v[54:57], v[204:207], v[152:155], v[54:57]
	v_mfma_f32_16x16x32_bf16 v[50:53], v[234:237], v[152:155], v[50:53]
	v_mfma_f32_16x16x32_bf16 v[38:41], v[204:207], v[160:163], v[38:41]
	v_mfma_f32_16x16x32_bf16 v[34:37], v[234:237], v[160:163], v[34:37]
	v_mfma_f32_16x16x32_bf16 v[22:25], v[204:207], v[188:191], v[22:25]
	v_mfma_f32_16x16x32_bf16 v[18:21], v[234:237], v[188:191], v[18:21]
	v_mfma_f32_16x16x32_bf16 v[6:9], v[204:207], v[196:199], v[6:9]
	v_mfma_f32_16x16x32_bf16 v[2:5], v[234:237], v[196:199], v[2:5]
	v_mfma_f32_16x16x32_bf16 v[54:57], v[208:211], v[156:159], v[54:57]
	v_mfma_f32_16x16x32_bf16 v[50:53], v[238:241], v[156:159], v[50:53]
	v_mfma_f32_16x16x32_bf16 v[38:41], v[208:211], v[184:187], v[38:41]
	v_mfma_f32_16x16x32_bf16 v[34:37], v[238:241], v[184:187], v[34:37]
	v_mfma_f32_16x16x32_bf16 v[22:25], v[208:211], v[192:195], v[22:25]
	v_mfma_f32_16x16x32_bf16 v[18:21], v[238:241], v[192:195], v[18:21]
	v_mfma_f32_16x16x32_bf16 v[6:9], v[208:211], v[200:203], v[6:9]
	v_mfma_f32_16x16x32_bf16 v[2:5], v[238:241], v[200:203], v[2:5]
	s_barrier
	s_add_i32 s4, 0, 0x18000
	ds_read_b128 v[136:139], v246
	ds_read_b128 v[140:143], v246 offset:1024
	ds_read_b128 v[144:147], v246 offset:2048
	ds_read_b128 v[148:151], v246 offset:3072
	s_mov_b32 m0, s64
	ds_read_b128 v[152:155], v233 offset:32768
	ds_read_b128 v[156:159], v233 offset:33792
	ds_read_b128 v[160:163], v233 offset:34816
	ds_read_b128 v[184:187], v233 offset:35840
	ds_read_b128 v[188:191], v233 offset:36864
	ds_read_b128 v[192:195], v233 offset:37888
	ds_read_b128 v[196:199], v233 offset:38912
	ds_read_b128 v[200:203], v233 offset:39936
	global_load_lds_dwordx4 v174, s[98:99]
	s_mov_b32 m0, s65
	s_nop 0
	global_load_lds_dwordx4 v176, s[98:99]
	s_waitcnt lgkmcnt(8)
	s_barrier
; #define PG8_STAGE(bufoff, gbase, voff) do { _Pragma("unroll") for (int _i = 0; _i < 2; ++_i) \
;         __builtin_amdgcn_global_load_lds((const unsigned*)((const char*)(gbase) + (voff)[_i]), (LAS unsigned*)(lds + (bufoff) + ldsw + _i * 8192), 16, 0, 0); } while (0)
; #define PG8_LDA(dst, b, h) do { _Pragma("unroll") for (int m = 0; m < 4; ++m) _Pragma("unroll") for (int k = 0; k < 2; ++k) dst[m][k] = *(const LAS bf16x8*)(lds + PG8_SA(b, h) + aoff + m * 2048 + k * 1024); } while (0)
; #define PG8_LDB(dst, b, h) do { _Pragma("unroll") for (int n = 0; n < 2; ++n) _Pragma("unroll") for (int k = 0; k < 2; ++k) dst[n][k] = *(const LAS bf16x8*)(lds + PG8_SB(b, h) + boff + n * 2048 + k * 1024); } while (0)
; #define PG8_MMA(ai, bj, At, Bt) do { __builtin_amdgcn_s_setprio(1); _Pragma("unroll") for (int m = 0; m < 4; ++m) _Pragma("unroll") for (int n = 0; n < 2; ++n) _Pragma("unroll") for (int k = 0; k < 2; ++k) \
;         acc[ai][bj][m][n] = __builtin_amdgcn_mfma_f32_16x16x32_bf16(Bt[n][k], At[m][k], acc[ai][bj][m][n], 0, 0, 0); __builtin_amdgcn_s_setprio(0); } while (0)
; #define PG8_WAIT_V(n) asm volatile("s_waitcnt vmcnt(" #n ")" ::: "memory")
; #define PG8_WAIT_L(n) asm volatile("s_waitcnt lgkmcnt(" #n ")" ::: "memory")
; #define PG8_BAR __builtin_amdgcn_s_barrier()
; #define PG8_SCHED __builtin_amdgcn_sched_barrier(0)
; __device__ __forceinline__ void gemm_epilogue(const GemmD& g, const f32x4 (&acc)[2][2][4][2], const Unit& u, int wr, int wc, int fr, int fq) {
;     const int row0 = u.pm * BM + wr * 64 + fr;
;     const int mode = g.mode;
;     if (u.part >= 0) {
; __device__ __forceinline__ void gemm_phase(LAS unsigned char* lds, const GemmD& g) {
;     ...
;             PG8_WAIT_L(8); PG8_BAR; PG8_WAIT_L(0); PG8_MMA(0, 0, At, B0); PG8_BAR; PG8_SCHED;
;             PG8_LDB(B1, 1, 1); PG8_STAGE(PG8_SB(1, 0), b3, voffB);
;             PG8_BAR; PG8_WAIT_L(0); PG8_MMA(0, 1, At, B1); PG8_BAR;
;             PG8_LDA(At, 1, 1); PG8_STAGE(PG8_SA(1, 0), a3, voffA);
;             PG8_BAR; PG8_WAIT_L(0); PG8_MMA(1, 0, At, B0); PG8_BAR; PG8_SCHED;
;             PG8_STAGE(PG8_SB(1, 1), b3 + hstep, voffB);
;             PG8_WAIT_V(6); PG8_BAR; PG8_MMA(1, 1, At, B1); PG8_BAR;
;         }
	s_waitcnt lgkmcnt(0)
	v_mfma_f32_16x16x32_bf16 v[126:129], v[136:139], v[152:155], v[126:129]
	v_mfma_f32_16x16x32_bf16 v[122:125], v[144:147], v[152:155], v[122:125]
	v_mfma_f32_16x16x32_bf16 v[110:113], v[136:139], v[160:163], v[110:113]
	v_mfma_f32_16x16x32_bf16 v[106:109], v[144:147], v[160:163], v[106:109]
	v_mfma_f32_16x16x32_bf16 v[94:97], v[136:139], v[188:191], v[94:97]
	v_mfma_f32_16x16x32_bf16 v[90:93], v[144:147], v[188:191], v[90:93]
	v_mfma_f32_16x16x32_bf16 v[78:81], v[136:139], v[196:199], v[78:81]
	v_mfma_f32_16x16x32_bf16 v[74:77], v[144:147], v[196:199], v[74:77]
	v_mfma_f32_16x16x32_bf16 v[126:129], v[140:143], v[156:159], v[126:129]
	v_mfma_f32_16x16x32_bf16 v[122:125], v[148:151], v[156:159], v[122:125]
	v_mfma_f32_16x16x32_bf16 v[110:113], v[140:143], v[184:187], v[110:113]
	v_mfma_f32_16x16x32_bf16 v[106:109], v[148:151], v[184:187], v[106:109]
	v_mfma_f32_16x16x32_bf16 v[94:97], v[140:143], v[192:195], v[94:97]
	v_mfma_f32_16x16x32_bf16 v[90:93], v[148:151], v[192:195], v[90:93]
	v_mfma_f32_16x16x32_bf16 v[78:81], v[140:143], v[200:203], v[78:81]
	v_mfma_f32_16x16x32_bf16 v[74:77], v[148:151], v[200:203], v[74:77]
	s_barrier
	s_add_i32 s6, 0, 0x1c000
	s_add_i32 s4, s4, s87
	ds_read_b128 v[204:207], v247
	ds_read_b128 v[208:211], v247 offset:1024
	ds_read_b128 v[234:237], v247 offset:2048
	ds_read_b128 v[238:241], v247 offset:3072
	s_add_u32 s100, s100, 0x80
	s_addc_u32 s101, s101, 0
	s_mov_b32 m0, s4
	s_nop 0
	global_load_lds_dwordx4 v172, s[100:101]
	s_add_i32 m0, s4, 0x2000
	s_nop 0
	global_load_lds_dwordx4 v168, s[100:101]
	s_barrier
	s_waitcnt lgkmcnt(0)
	v_mfma_f32_16x16x32_bf16 v[118:121], v[204:207], v[152:155], v[118:121]
	v_mfma_f32_16x16x32_bf16 v[114:117], v[234:237], v[152:155], v[114:117]
	v_mfma_f32_16x16x32_bf16 v[102:105], v[204:207], v[160:163], v[102:105]
	v_mfma_f32_16x16x32_bf16 v[98:101], v[234:237], v[160:163], v[98:101]
	v_mfma_f32_16x16x32_bf16 v[86:89], v[204:207], v[188:191], v[86:89]
	v_mfma_f32_16x16x32_bf16 v[82:85], v[234:237], v[188:191], v[82:85]
	v_mfma_f32_16x16x32_bf16 v[70:73], v[204:207], v[196:199], v[70:73]
	v_mfma_f32_16x16x32_bf16 v[66:69], v[234:237], v[196:199], v[66:69]
	v_mfma_f32_16x16x32_bf16 v[118:121], v[208:211], v[156:159], v[118:121]
	v_mfma_f32_16x16x32_bf16 v[114:117], v[238:241], v[156:159], v[114:117]
	v_mfma_f32_16x16x32_bf16 v[102:105], v[208:211], v[184:187], v[102:105]
	v_mfma_f32_16x16x32_bf16 v[98:101], v[238:241], v[184:187], v[98:101]
	v_mfma_f32_16x16x32_bf16 v[86:89], v[208:211], v[192:195], v[86:89]
	v_mfma_f32_16x16x32_bf16 v[82:85], v[238:241], v[192:195], v[82:85]
	v_mfma_f32_16x16x32_bf16 v[70:73], v[208:211], v[200:203], v[70:73]
	v_mfma_f32_16x16x32_bf16 v[66:69], v[238:241], v[200:203], v[66:69]
	s_barrier
	s_mov_b32 m0, s28
	s_add_u32 s98, s98, 0x80
	s_addc_u32 s99, s99, 0
	ds_read_b128 v[152:155], v233 offset:49152
	ds_read_b128 v[156:159], v233 offset:50176
	ds_read_b128 v[160:163], v233 offset:51200
	ds_read_b128 v[184:187], v233 offset:52224
	ds_read_b128 v[188:191], v233 offset:53248
	ds_read_b128 v[192:195], v233 offset:54272
	ds_read_b128 v[196:199], v233 offset:55296
	ds_read_b128 v[200:203], v233 offset:56320
	global_load_lds_dwordx4 v170, s[98:99]
	s_mov_b32 m0, s29
	s_nop 0
	global_load_lds_dwordx4 v166, s[98:99]
	s_barrier
	s_waitcnt lgkmcnt(0)
	v_mfma_f32_16x16x32_bf16 v[62:65], v[136:139], v[152:155], v[62:65]
	v_mfma_f32_16x16x32_bf16 v[58:61], v[144:147], v[152:155], v[58:61]
	v_mfma_f32_16x16x32_bf16 v[46:49], v[136:139], v[160:163], v[46:49]
	v_mfma_f32_16x16x32_bf16 v[42:45], v[144:147], v[160:163], v[42:45]
	v_mfma_f32_16x16x32_bf16 v[30:33], v[136:139], v[188:191], v[30:33]
	v_mfma_f32_16x16x32_bf16 v[26:29], v[144:147], v[188:191], v[26:29]
	v_mfma_f32_16x16x32_bf16 v[14:17], v[136:139], v[196:199], v[14:17]
	v_mfma_f32_16x16x32_bf16 v[10:13], v[144:147], v[196:199], v[10:13]
	v_mfma_f32_16x16x32_bf16 v[62:65], v[140:143], v[156:159], v[62:65]
	v_mfma_f32_16x16x32_bf16 v[58:61], v[148:151], v[156:159], v[58:61]
	v_mfma_f32_16x16x32_bf16 v[46:49], v[140:143], v[184:187], v[46:49]
	v_mfma_f32_16x16x32_bf16 v[42:45], v[148:151], v[184:187], v[42:45]
	v_mfma_f32_16x16x32_bf16 v[30:33], v[140:143], v[192:195], v[30:33]
	v_mfma_f32_16x16x32_bf16 v[26:29], v[148:151], v[192:195], v[26:29]
	v_mfma_f32_16x16x32_bf16 v[14:17], v[140:143], v[200:203], v[14:17]
	v_mfma_f32_16x16x32_bf16 v[10:13], v[148:151], v[200:203], v[10:13]
	s_barrier
	s_add_i32 s4, s6, s87
	s_mov_b32 m0, s4
	s_nop 0
	global_load_lds_dwordx4 v242, s[100:101]
	s_add_i32 m0, s4, 0x2000
	s_nop 0
	global_load_lds_dwordx4 v243, s[100:101]
	s_add_u32 s100, s100, 0x80
	s_addc_u32 s101, s101, 0
	s_mov_b32 s4, s5
	s_waitcnt vmcnt(6)
	s_barrier
	v_mfma_f32_16x16x32_bf16 v[54:57], v[204:207], v[152:155], v[54:57]
	v_mfma_f32_16x16x32_bf16 v[50:53], v[234:237], v[152:155], v[50:53]
	v_mfma_f32_16x16x32_bf16 v[38:41], v[204:207], v[160:163], v[38:41]
	v_mfma_f32_16x16x32_bf16 v[34:37], v[234:237], v[160:163], v[34:37]
	v_mfma_f32_16x16x32_bf16 v[22:25], v[204:207], v[188:191], v[22:25]
	v_mfma_f32_16x16x32_bf16 v[18:21], v[234:237], v[188:191], v[18:21]
	v_mfma_f32_16x16x32_bf16 v[6:9], v[204:207], v[196:199], v[6:9]
	v_mfma_f32_16x16x32_bf16 v[2:5], v[234:237], v[196:199], v[2:5]
	v_mfma_f32_16x16x32_bf16 v[54:57], v[208:211], v[156:159], v[54:57]
	v_mfma_f32_16x16x32_bf16 v[50:53], v[238:241], v[156:159], v[50:53]
	v_mfma_f32_16x16x32_bf16 v[38:41], v[208:211], v[184:187], v[38:41]
	v_mfma_f32_16x16x32_bf16 v[34:37], v[238:241], v[184:187], v[34:37]
	v_mfma_f32_16x16x32_bf16 v[22:25], v[208:211], v[192:195], v[22:25]
	v_mfma_f32_16x16x32_bf16 v[18:21], v[238:241], v[192:195], v[18:21]
	v_mfma_f32_16x16x32_bf16 v[6:9], v[208:211], v[200:203], v[6:9]
	v_mfma_f32_16x16x32_bf16 v[2:5], v[238:241], v[200:203], v[2:5]
	s_cbranch_vccz .LBB0_145
	s_barrier
	v_lshl_add_u32 v184, s56, 8, v228
	s_cmp_lt_i32 s66, 0
	s_mov_b64 s[4:5], -1
	s_cbranch_scc0 .LBB0_704
